# attention unit prologue de-serialised: the 8 K/V staging loads and first q/gate/sink loads issued together with counted waits; V transposed into LDS with paired 32-bit writes
# baseline (speedup 1.0000x reference)
.LBB0_757:
	s_ashr_i32 s0, s38, 1
	s_and_b32 s24, s38, 1
	s_cmp_gt_i32 s0, 0
	s_cselect_b64 s[20:21], -1, 0
	s_lshl_b32 s25, s0, 7
	s_add_i32 s26, s25, 0xffffff80
	s_lshl_b32 s22, s24, 6
	s_lshl_b32 s14, s22, 1
	s_or_b64 s[98:99], s[20:21], s[16:17]
	s_or_b64 s[100:101], s[20:21], s[2:3]
	v_mov_b32_e32 v67, v55
	v_and_b32_e32 v184, 1, v0
	v_mov_b32_e32 v185, 0xfdfe0606
	v_mul_lo_u32 v182, v184, v185
	v_add_u32_e32 v182, 0x5040100, v182
	v_mul_u32_u24_e32 v183, 0x20e, v184
	v_add_u32_e32 v178, s26, v59
	v_mov_b64_e32 v[176:177], s[18:19]
	v_mad_i64_i32 v[176:177], s[22:23], v178, s36, v[176:177]
	v_lshl_add_u64 v[176:177], v[176:177], 0, s[14:15]
	v_lshl_add_u64 v[176:177], v[176:177], 0, v[66:67]
	global_load_dwordx4 v[144:147], v[176:177], off offset:2048
	v_add_u32_sdwa v178, s26, v0 dst_sel:DWORD dst_unused:UNUSED_PAD src0_sel:DWORD src1_sel:BYTE_0
	v_mov_b64_e32 v[180:181], s[18:19]
	v_mad_i64_i32 v[180:181], s[22:23], v178, s36, v[180:181]
	v_lshl_add_u64 v[180:181], v[180:181], 0, s[14:15]
	v_mov_b32_e32 v63, v55
	v_lshl_add_u64 v[176:177], v[180:181], 0, v[62:63]
	global_load_dwordx4 v[148:151], v[176:177], off offset:2304
	v_add_u32_e32 v178, s26, v94
	v_mov_b64_e32 v[176:177], s[18:19]
	v_mad_i64_i32 v[176:177], s[22:23], v178, s36, v[176:177]
	v_lshl_add_u64 v[176:177], v[176:177], 0, s[14:15]
	v_lshl_add_u64 v[176:177], v[176:177], 0, v[66:67]
	global_load_dwordx4 v[152:155], v[176:177], off offset:2048
	v_mov_b32_e32 v65, v55
	v_lshl_add_u64 v[176:177], v[180:181], 0, v[64:65]
	global_load_dwordx4 v[156:159], v[176:177], off offset:2304
	v_add_u32_e32 v178, s26, v95
	v_mov_b64_e32 v[176:177], s[18:19]
	v_mad_i64_i32 v[176:177], s[22:23], v178, s36, v[176:177]
	v_lshl_add_u64 v[176:177], v[176:177], 0, s[14:15]
	v_lshl_add_u64 v[176:177], v[176:177], 0, v[66:67]
	global_load_dwordx4 v[160:163], v[176:177], off offset:2048
	v_mov_b32_e32 v69, v55
	v_lshl_add_u64 v[176:177], v[180:181], 0, v[68:69]
	global_load_dwordx4 v[164:167], v[176:177], off offset:2304
	v_add_u32_e32 v178, s26, v96
	v_mov_b64_e32 v[176:177], s[18:19]
	v_mad_i64_i32 v[176:177], s[22:23], v178, s36, v[176:177]
	v_lshl_add_u64 v[176:177], v[176:177], 0, s[14:15]
	v_lshl_add_u64 v[176:177], v[176:177], 0, v[66:67]
	global_load_dwordx4 v[168:171], v[176:177], off offset:2048
	v_mov_b32_e32 v71, v55
	v_lshl_add_u64 v[176:177], v[180:181], 0, v[70:71]
	global_load_dwordx4 v[172:175], v[176:177], off offset:2304
	s_mov_b32 s14, 0
	v_lshl_or_b32 v8, s24, 3, v1
	v_or_b32_e32 v63, s25, v97
	v_mov_b64_e32 v[2:3], s[18:19]
	v_mad_i64_i32 v[2:3], s[0:1], v63, s36, v[2:3]
	v_lshlrev_b32_e32 v4, 7, v8
	v_mov_b32_e32 v5, v55
	v_lshl_add_u64 v[2:3], v[2:3], 0, v[4:5]
	v_lshlrev_b32_e32 v54, 1, v56
	v_mov_b32_e32 v73, v55
	v_lshl_add_u64 v[6:7], v[2:3], 0, v[54:55]
	v_lshl_add_u64 v[2:3], v[2:3], 0, v[72:73]
	global_load_dwordx2 v[92:93], v[2:3], off offset:2560
	global_load_dwordx2 v[90:91], v[2:3], off offset:2592
	global_load_dwordx2 v[84:85], v[2:3], off offset:2624
	global_load_dwordx2 v[76:77], v[2:3], off offset:2656
	global_load_dwordx4 v[50:53], v[6:7], off
	global_load_dwordx4 v[46:49], v[6:7], off offset:64
	v_lshlrev_b32_e32 v2, 2, v8
	global_load_dword v65, v2, s[80:81]
	s_waitcnt vmcnt(14)
	v_cndmask_b32_e64 v144, 0, v144, s[20:21]
	v_cndmask_b32_e64 v145, 0, v145, s[20:21]
	v_cndmask_b32_e64 v146, 0, v146, s[20:21]
	v_cndmask_b32_e64 v147, 0, v147, s[20:21]
	ds_write_b128 v113, v[144:147]
	s_waitcnt vmcnt(13)
	v_cndmask_b32_e64 v148, 0, v148, s[98:99]
	v_cndmask_b32_e64 v149, 0, v149, s[98:99]
	v_cndmask_b32_e64 v150, 0, v150, s[98:99]
	v_cndmask_b32_e64 v151, 0, v151, s[98:99]
	s_nop 1
	v_mov_b32_dpp v186, v148 quad_perm:[1,0,3,2] row_mask:0xf bank_mask:0xf
	v_mov_b32_dpp v187, v149 quad_perm:[1,0,3,2] row_mask:0xf bank_mask:0xf
	v_mov_b32_dpp v188, v150 quad_perm:[1,0,3,2] row_mask:0xf bank_mask:0xf
	v_mov_b32_dpp v189, v151 quad_perm:[1,0,3,2] row_mask:0xf bank_mask:0xf
	v_perm_b32 v186, v186, v148, v182
	v_perm_b32 v187, v187, v149, v182
	v_perm_b32 v188, v188, v150, v182
	v_perm_b32 v189, v189, v151, v182
	v_add_u32_e32 v190, v183, v114
	ds_write_b32 v190, v186 offset:36864
	ds_write_b32 v190, v187 offset:37920
	ds_write_b32 v190, v188 offset:38976
	ds_write_b32 v190, v189 offset:40032
	s_waitcnt vmcnt(12)
	v_cndmask_b32_e64 v152, 0, v152, s[100:101]
	v_cndmask_b32_e64 v153, 0, v153, s[100:101]
	v_cndmask_b32_e64 v154, 0, v154, s[100:101]
	v_cndmask_b32_e64 v155, 0, v155, s[100:101]
	ds_write_b128 v115, v[152:155]
	s_waitcnt vmcnt(11)
	v_cndmask_b32_e64 v156, 0, v156, s[98:99]
	v_cndmask_b32_e64 v157, 0, v157, s[98:99]
	v_cndmask_b32_e64 v158, 0, v158, s[98:99]
	v_cndmask_b32_e64 v159, 0, v159, s[98:99]
	s_nop 1
	v_mov_b32_dpp v186, v156 quad_perm:[1,0,3,2] row_mask:0xf bank_mask:0xf
	v_mov_b32_dpp v187, v157 quad_perm:[1,0,3,2] row_mask:0xf bank_mask:0xf
	v_mov_b32_dpp v188, v158 quad_perm:[1,0,3,2] row_mask:0xf bank_mask:0xf
	v_mov_b32_dpp v189, v159 quad_perm:[1,0,3,2] row_mask:0xf bank_mask:0xf
	v_perm_b32 v186, v186, v156, v182
	v_perm_b32 v187, v187, v157, v182
	v_perm_b32 v188, v188, v158, v182
	v_perm_b32 v189, v189, v159, v182
	v_add_u32_e32 v190, v183, v116
	ds_write_b32 v190, v186 offset:36864
	ds_write_b32 v190, v187 offset:37920
	ds_write_b32 v190, v188 offset:38976
	ds_write_b32 v190, v189 offset:40032
	s_waitcnt vmcnt(10)
	ds_write_b128 v117, v[160:163]
	s_waitcnt vmcnt(9)
	v_cndmask_b32_e64 v164, 0, v164, s[98:99]
	v_cndmask_b32_e64 v165, 0, v165, s[98:99]
	v_cndmask_b32_e64 v166, 0, v166, s[98:99]
	v_cndmask_b32_e64 v167, 0, v167, s[98:99]
	s_nop 1
	v_mov_b32_dpp v186, v164 quad_perm:[1,0,3,2] row_mask:0xf bank_mask:0xf
	v_mov_b32_dpp v187, v165 quad_perm:[1,0,3,2] row_mask:0xf bank_mask:0xf
	v_mov_b32_dpp v188, v166 quad_perm:[1,0,3,2] row_mask:0xf bank_mask:0xf
	v_mov_b32_dpp v189, v167 quad_perm:[1,0,3,2] row_mask:0xf bank_mask:0xf
	v_perm_b32 v186, v186, v164, v182
	v_perm_b32 v187, v187, v165, v182
	v_perm_b32 v188, v188, v166, v182
	v_perm_b32 v189, v189, v167, v182
	v_add_u32_e32 v190, v183, v118
	ds_write_b32 v190, v186 offset:36864
	ds_write_b32 v190, v187 offset:37920
	ds_write_b32 v190, v188 offset:38976
	ds_write_b32 v190, v189 offset:40032
	s_waitcnt vmcnt(8)
	ds_write_b128 v119, v[168:171]
	s_waitcnt vmcnt(7)
	v_cndmask_b32_e64 v172, 0, v172, s[98:99]
	v_cndmask_b32_e64 v173, 0, v173, s[98:99]
	v_cndmask_b32_e64 v174, 0, v174, s[98:99]
	v_cndmask_b32_e64 v175, 0, v175, s[98:99]
	s_nop 1
	v_mov_b32_dpp v186, v172 quad_perm:[1,0,3,2] row_mask:0xf bank_mask:0xf
	v_mov_b32_dpp v187, v173 quad_perm:[1,0,3,2] row_mask:0xf bank_mask:0xf
	v_mov_b32_dpp v188, v174 quad_perm:[1,0,3,2] row_mask:0xf bank_mask:0xf
	v_mov_b32_dpp v189, v175 quad_perm:[1,0,3,2] row_mask:0xf bank_mask:0xf
	v_perm_b32 v186, v186, v172, v182
	v_perm_b32 v187, v187, v173, v182
	v_perm_b32 v188, v188, v174, v182
	v_perm_b32 v189, v189, v175, v182
	v_add_u32_e32 v190, v183, v120
	ds_write_b32 v190, v186 offset:36864
	ds_write_b32 v190, v187 offset:37920
	ds_write_b32 v190, v188 offset:38976
	ds_write_b32 v190, v189 offset:40032
	s_waitcnt lgkmcnt(0)
	s_barrier
	v_lshl_add_u64 v[74:75], v[60:61], 0, v[4:5]
	v_lshl_add_u64 v[78:79], s[18:19], 0, v[4:5]
	s_mov_b32 s39, 0
	s_waitcnt vmcnt(6)
	v_mov_b64_e32 v[80:81], v[92:93]
	s_waitcnt vmcnt(5)
	v_mov_b64_e32 v[82:83], v[90:91]
	s_waitcnt vmcnt(4)
	v_mov_b64_e32 v[86:87], v[84:85]
	s_waitcnt vmcnt(3)
	v_mov_b64_e32 v[88:89], v[76:77]
	s_waitcnt vmcnt(2)
	v_mov_b64_e32 v[6:7], v[50:51]
	s_waitcnt vmcnt(1)
	v_mov_b64_e32 v[2:3], v[46:47]
	v_mov_b64_e32 v[4:5], v[48:49]
	v_mov_b64_e32 v[8:9], v[52:53]
	s_branch .LBB0_773
